# v73 + hand-written QKV GEMM epilogue (butterfly reduce-scatter rstd + QK-norm, 460 vs 948 instr)
# speedup vs baseline: 1.0064x; 1.0064x over previous
; __device__ __forceinline__ void load_rstd(const float* ssq, int row0, int fq, float (&rs)[2][4]) {
; #pragma unroll
;     for (int ai = 0; ai < 2; ++ai)
; #pragma unroll
;         for (int m = 0; m < 4; ++m) {
;             const f32x4 v = *(const f32x4*)(ssq + (size_t)(row0 + ai * HALF + m * 16) * 16 + 4 * fq);
;             float s = (v[0] + v[1]) + (v[2] + v[3]);
;             s += shx<16>(s); s += shx<32>(s);
;             rs[ai][m] = rsqrtf(s * (1.0f / 1024.0f) + RMS_EPS_F);
;         }
; }
;     __device__ __forceinline__ void operator()(const f32x4 (&acc)[2][2][4][2], const Unit& u, int wr, int wc, int fr, int fq) const {
;         const int buf = u.pn >> 2, pl = u.pn & 3;
;         const int row0 = u.pm * BM + wr * 64 + fr;
;         const int colbase = 256 * pl + 64 * wc + 8 * fq;
;         bf16_t* base = Q + (size_t)buf * (size_t)(32u << 20);
;         const bool norm = (buf < 2) && (odd || pl >= 2);
;         const float sc = (buf == 0) ? C2_F : 1.0f;
;         const float* g = gq + ((buf == 0) ? 0 : (gk - gq));
;         const f32x4 one4 = (f32x4){1.f, 1.f, 1.f, 1.f};
;         const float* gp = g + 8 * fq;
;         const f32x4 g00 = (norm ? *(const f32x4*)(gp) : one4) * sc, g01 = (norm ? *(const f32x4*)(gp + 4) : one4) * sc;
;         const f32x4 g10 = (norm ? *(const f32x4*)(gp + 32) : one4) * sc, g11 = (norm ? *(const f32x4*)(gp + 36) : one4) * sc;
;         float rs[2][4]; load_rstd(ssq, row0, fq, rs);
; #pragma unroll
;         for (int ai = 0; ai < 2; ++ai)
; #pragma unroll
;             for (int m = 0; m < 4; ++m) {
;                 float mul = rs[ai][m];
;                 if (norm) {
;                     float ss = 0.f;
; #pragma unroll
;                     for (int bj = 0; bj < 2; ++bj)
; #pragma unroll
;                         for (int n = 0; n < 2; ++n) { const f32x4 x = acc[ai][bj][m][n]; ss += (x[0] * x[0] + x[1] * x[1]) + (x[2] * x[2] + x[3] * x[3]); }
;                     ss += shx<16>(ss); ss += shx<32>(ss);
;                     mul *= rsqrtf(ss * mul * mul * (1.0f / 64.0f) + RMS_EPS_F);
.LBB0_103:
	s_ashr_i32 s28, s6, 2
	s_and_b32 s3, s6, 3
	s_cmp_lt_i32 s28, 2
	s_cselect_b64 s[8:9], -1, 0
	s_cmp_gt_u32 s3, 1
	s_cselect_b64 s[30:31], -1, 0
	s_or_b64 s[30:31], s[16:17], s[30:31]
	s_and_b64 s[30:31], s[8:9], s[30:31]
	s_cmp_lt_u32 s6, 4
	s_cselect_b64 s[8:9], -1, 0
	s_and_b64 s[6:7], s[8:9], exec
	s_cselect_b32 s7, 0, s19
	s_cselect_b32 s6, 0, s18
	v_lshl_add_u32 v202, s10, 8, v3
	v_lshl_add_u64 v[164:165], s[6:7], 2, v[174:175]
	s_ashr_i32 s29, s28, 31
	s_lshl_b64 s[10:11], s[28:29], 26
	s_add_u32 s10, s48, s10
	s_addc_u32 s11, s49, s11
	s_and_b64 vcc, exec, s[30:31]
	s_cbranch_vccz .Lqe_g1
	global_load_dwordx4 v[132:135], v[164:165], off
	global_load_dwordx4 v[136:139], v[164:165], off offset:16
	global_load_dwordx4 v[140:143], v[164:165], off offset:128
	global_load_dwordx4 v[144:147], v[164:165], off offset:144
.Lqe_g1:
	v_lshlrev_b32_e32 v192, 6, v202
	v_mov_b32_e32 v193, v2
	v_lshl_add_u64 v[194:195], v[176:177], 0, v[192:193]
	s_mov_b32 s100, 0x2000
	s_mov_b32 s101, 0
	v_lshl_add_u64 v[198:199], v[194:195], 0, s[100:101]
	global_load_dwordx4 v[148:151], v[194:195], off
	global_load_dwordx4 v[152:155], v[194:195], off offset:1024
	global_load_dwordx4 v[156:159], v[194:195], off offset:2048
	global_load_dwordx4 v[160:163], v[194:195], off offset:3072
	global_load_dwordx4 v[208:211], v[198:199], off
	global_load_dwordx4 v[212:215], v[198:199], off offset:1024
	global_load_dwordx4 v[216:219], v[198:199], off offset:2048
	global_load_dwordx4 v[220:223], v[198:199], off offset:3072
	v_lshl_or_b32 v192, s3, 9, v206
	v_lshl_add_u32 v192, v202, 11, v192
	v_lshl_add_u64 v[166:167], s[10:11], 0, v[192:193]
	s_waitcnt vmcnt(7)
	v_add_f32_e32 v182, v148, v149
	v_add_f32_e32 v150, v150, v151
	v_add_f32_e32 v182, v182, v150
	s_waitcnt vmcnt(6)
	v_add_f32_e32 v183, v152, v153
	v_add_f32_e32 v154, v154, v155
	v_add_f32_e32 v183, v183, v154
	s_waitcnt vmcnt(5)
	v_add_f32_e32 v184, v156, v157
	v_add_f32_e32 v158, v158, v159
	v_add_f32_e32 v184, v184, v158
	s_waitcnt vmcnt(4)
	v_add_f32_e32 v185, v160, v161
	v_add_f32_e32 v162, v162, v163
	v_add_f32_e32 v185, v185, v162
	s_waitcnt vmcnt(3)
	v_add_f32_e32 v186, v208, v209
	v_add_f32_e32 v210, v210, v211
	v_add_f32_e32 v186, v186, v210
	s_waitcnt vmcnt(2)
	v_add_f32_e32 v187, v212, v213
	v_add_f32_e32 v214, v214, v215
	v_add_f32_e32 v187, v187, v214
	s_waitcnt vmcnt(1)
	v_add_f32_e32 v188, v216, v217
	v_add_f32_e32 v218, v218, v219
	v_add_f32_e32 v188, v188, v218
	s_waitcnt vmcnt(0)
	v_add_f32_e32 v189, v220, v221
	v_add_f32_e32 v222, v222, v223
	v_add_f32_e32 v189, v189, v222
	s_nop 1
	v_permlane32_swap_b32_e32 v182, v183
	v_permlane32_swap_b32_e32 v184, v185
	v_permlane32_swap_b32_e32 v186, v187
	v_permlane32_swap_b32_e32 v188, v189
	v_add_f32_e32 v182, v182, v183
	v_add_f32_e32 v184, v184, v185
	v_add_f32_e32 v186, v186, v187
	v_add_f32_e32 v188, v188, v189
	s_nop 1
	v_permlane16_swap_b32_e32 v182, v184
	v_permlane16_swap_b32_e32 v186, v188
	v_add_f32_e32 v182, v182, v184
	v_add_f32_e32 v186, v186, v188
	v_fmamk_f32 v190, v182, 0x3a800000, v196
	v_fmamk_f32 v191, v186, 0x3a800000, v196
	v_rsq_f32_e32 v190, v190
	v_rsq_f32_e32 v191, v191
	s_and_b64 vcc, exec, s[30:31]
	s_cbranch_vccz .Lqe_nn
	v_mov_b32_e32 v192, 0x3e38aa3b
	v_cndmask_b32_e64 v192, 1.0, v192, s[8:9]
	v_pk_mul_f32 v[132:133], v[192:193], v[132:133] op_sel_hi:[0,1]
	v_pk_mul_f32 v[134:135], v[192:193], v[134:135] op_sel_hi:[0,1]
	v_pk_mul_f32 v[136:137], v[192:193], v[136:137] op_sel_hi:[0,1]
	v_pk_mul_f32 v[138:139], v[192:193], v[138:139] op_sel_hi:[0,1]
	v_pk_mul_f32 v[140:141], v[192:193], v[140:141] op_sel_hi:[0,1]
	v_pk_mul_f32 v[142:143], v[192:193], v[142:143] op_sel_hi:[0,1]
	v_pk_mul_f32 v[144:145], v[192:193], v[144:145] op_sel_hi:[0,1]
	v_pk_mul_f32 v[146:147], v[192:193], v[146:147] op_sel_hi:[0,1]
	v_pk_mul_f32 v[216:217], v[128:129], v[128:129]
	v_pk_mul_f32 v[218:219], v[130:131], v[130:131]
	v_pk_mul_f32 v[220:221], v[112:113], v[112:113]
	v_pk_mul_f32 v[222:223], v[114:115], v[114:115]
	v_pk_fma_f32 v[216:217], v[124:125], v[124:125], v[216:217]
	v_pk_fma_f32 v[218:219], v[126:127], v[126:127], v[218:219]
	v_pk_fma_f32 v[220:221], v[108:109], v[108:109], v[220:221]
	v_pk_fma_f32 v[222:223], v[110:111], v[110:111], v[222:223]
	v_pk_fma_f32 v[216:217], v[120:121], v[120:121], v[216:217]
	v_pk_fma_f32 v[218:219], v[122:123], v[122:123], v[218:219]
	v_pk_fma_f32 v[220:221], v[104:105], v[104:105], v[220:221]
	v_pk_fma_f32 v[222:223], v[106:107], v[106:107], v[222:223]
	v_pk_fma_f32 v[216:217], v[116:117], v[116:117], v[216:217]
	v_pk_fma_f32 v[218:219], v[118:119], v[118:119], v[218:219]
	v_pk_fma_f32 v[220:221], v[100:101], v[100:101], v[220:221]
	v_pk_fma_f32 v[222:223], v[102:103], v[102:103], v[222:223]
	v_pk_add_f32 v[216:217], v[216:217], v[218:219]
	v_pk_add_f32 v[220:221], v[220:221], v[222:223]
	v_add_f32_e32 v208, v216, v217
	v_add_f32_e32 v209, v220, v221
	v_pk_mul_f32 v[216:217], v[96:97], v[96:97]
	v_pk_mul_f32 v[218:219], v[98:99], v[98:99]
	v_pk_mul_f32 v[220:221], v[80:81], v[80:81]
	v_pk_mul_f32 v[222:223], v[82:83], v[82:83]
	v_pk_fma_f32 v[216:217], v[92:93], v[92:93], v[216:217]
	v_pk_fma_f32 v[218:219], v[94:95], v[94:95], v[218:219]
	v_pk_fma_f32 v[220:221], v[76:77], v[76:77], v[220:221]
	v_pk_fma_f32 v[222:223], v[78:79], v[78:79], v[222:223]
	v_pk_fma_f32 v[216:217], v[88:89], v[88:89], v[216:217]
	v_pk_fma_f32 v[218:219], v[90:91], v[90:91], v[218:219]
	v_pk_fma_f32 v[220:221], v[72:73], v[72:73], v[220:221]
	v_pk_fma_f32 v[222:223], v[74:75], v[74:75], v[222:223]
	v_pk_fma_f32 v[216:217], v[84:85], v[84:85], v[216:217]
	v_pk_fma_f32 v[218:219], v[86:87], v[86:87], v[218:219]
;     __device__ __forceinline__ void operator()(const f32x4 (&acc)[2][2][4][2], const Unit& u, int wr, int wc, int fr, int fq) const {
;     ...
;                     float ss = 0.f;
; #pragma unroll
;                     for (int bj = 0; bj < 2; ++bj)
; #pragma unroll
;                         for (int n = 0; n < 2; ++n) { const f32x4 x = acc[ai][bj][m][n]; ss += (x[0] * x[0] + x[1] * x[1]) + (x[2] * x[2] + x[3] * x[3]); }
;                     ss += shx<16>(ss); ss += shx<32>(ss);
;                     mul *= rsqrtf(ss * mul * mul * (1.0f / 64.0f) + RMS_EPS_F);
;                 }
	v_pk_fma_f32 v[220:221], v[68:69], v[68:69], v[220:221]
	v_pk_fma_f32 v[222:223], v[70:71], v[70:71], v[222:223]
	v_pk_add_f32 v[216:217], v[216:217], v[218:219]
	v_pk_add_f32 v[220:221], v[220:221], v[222:223]
	v_add_f32_e32 v210, v216, v217
	v_add_f32_e32 v211, v220, v221
	v_pk_mul_f32 v[216:217], v[64:65], v[64:65]
	v_pk_mul_f32 v[218:219], v[66:67], v[66:67]
	v_pk_mul_f32 v[220:221], v[48:49], v[48:49]
	v_pk_mul_f32 v[222:223], v[50:51], v[50:51]
	v_pk_fma_f32 v[216:217], v[60:61], v[60:61], v[216:217]
	v_pk_fma_f32 v[218:219], v[62:63], v[62:63], v[218:219]
	v_pk_fma_f32 v[220:221], v[44:45], v[44:45], v[220:221]
	v_pk_fma_f32 v[222:223], v[46:47], v[46:47], v[222:223]
	v_pk_fma_f32 v[216:217], v[56:57], v[56:57], v[216:217]
	v_pk_fma_f32 v[218:219], v[58:59], v[58:59], v[218:219]
	v_pk_fma_f32 v[220:221], v[40:41], v[40:41], v[220:221]
	v_pk_fma_f32 v[222:223], v[42:43], v[42:43], v[222:223]
	v_pk_fma_f32 v[216:217], v[52:53], v[52:53], v[216:217]
	v_pk_fma_f32 v[218:219], v[54:55], v[54:55], v[218:219]
	v_pk_fma_f32 v[220:221], v[36:37], v[36:37], v[220:221]
	v_pk_fma_f32 v[222:223], v[38:39], v[38:39], v[222:223]
	v_pk_add_f32 v[216:217], v[216:217], v[218:219]
	v_pk_add_f32 v[220:221], v[220:221], v[222:223]
	v_add_f32_e32 v212, v216, v217
	v_add_f32_e32 v213, v220, v221
	v_pk_mul_f32 v[216:217], v[32:33], v[32:33]
	v_pk_mul_f32 v[218:219], v[34:35], v[34:35]
	v_pk_mul_f32 v[220:221], v[16:17], v[16:17]
	v_pk_mul_f32 v[222:223], v[18:19], v[18:19]
	v_pk_fma_f32 v[216:217], v[28:29], v[28:29], v[216:217]
	v_pk_fma_f32 v[218:219], v[30:31], v[30:31], v[218:219]
	v_pk_fma_f32 v[220:221], v[12:13], v[12:13], v[220:221]
	v_pk_fma_f32 v[222:223], v[14:15], v[14:15], v[222:223]
	v_pk_fma_f32 v[216:217], v[24:25], v[24:25], v[216:217]
	v_pk_fma_f32 v[218:219], v[26:27], v[26:27], v[218:219]
	v_pk_fma_f32 v[220:221], v[8:9], v[8:9], v[220:221]
	v_pk_fma_f32 v[222:223], v[10:11], v[10:11], v[222:223]
	v_pk_fma_f32 v[216:217], v[20:21], v[20:21], v[216:217]
	v_pk_fma_f32 v[218:219], v[22:23], v[22:23], v[218:219]
	v_pk_fma_f32 v[220:221], v[4:5], v[4:5], v[220:221]
	v_pk_fma_f32 v[222:223], v[6:7], v[6:7], v[222:223]
	v_pk_add_f32 v[216:217], v[216:217], v[218:219]
	v_pk_add_f32 v[220:221], v[220:221], v[222:223]
	v_add_f32_e32 v214, v216, v217
	v_add_f32_e32 v215, v220, v221
	s_nop 1
	v_permlane32_swap_b32_e32 v208, v209
	v_permlane32_swap_b32_e32 v210, v211
	v_permlane32_swap_b32_e32 v212, v213
	v_permlane32_swap_b32_e32 v214, v215
	v_add_f32_e32 v208, v208, v209
	v_add_f32_e32 v210, v210, v211
	v_add_f32_e32 v212, v212, v213
	v_add_f32_e32 v214, v214, v215
	s_nop 1
	v_permlane16_swap_b32_e32 v208, v210
	v_permlane16_swap_b32_e32 v212, v214
	v_add_f32_e32 v208, v208, v210
	v_add_f32_e32 v212, v212, v214
	v_mul_f32_e32 v208, v190, v208
	v_mul_f32_e32 v212, v191, v212
	v_mul_f32_e32 v208, v190, v208
	v_mul_f32_e32 v212, v191, v212
	v_fmamk_f32 v208, v208, 0x3c800000, v196
	v_fmamk_f32 v212, v212, 0x3c800000, v196
	v_rsq_f32_e32 v208, v208
	v_rsq_f32_e32 v212, v212
	s_nop 0
	v_mul_f32_e32 v190, v190, v208
	v_mul_f32_e32 v191, v191, v212
.Lqe_nn:
	s_nop 0
	v_mov_b32_e32 v207, v190
	s_nop 1
	v_permlane16_swap_b32_e32 v190, v207
	v_mov_b32_e32 v148, v190
	v_mov_b32_e32 v152, v207
	v_mov_b32_e32 v150, v190
	v_mov_b32_e32 v154, v207
	s_nop 1
	v_permlane32_swap_b32_e32 v148, v150
	v_permlane32_swap_b32_e32 v152, v154
	v_mov_b32_e32 v207, v191
	s_nop 1
	v_permlane16_swap_b32_e32 v191, v207
	v_mov_b32_e32 v156, v191
	v_mov_b32_e32 v160, v207
	v_mov_b32_e32 v158, v191
	v_mov_b32_e32 v162, v207
	s_nop 1
	v_permlane32_swap_b32_e32 v156, v158
	v_permlane32_swap_b32_e32 v160, v162
	s_or_b64 s[6:7], s[30:31], s[8:9]
	s_and_b64 vcc, exec, s[6:7]
	s_cbranch_vccz .Lqe_plain
	s_and_b64 vcc, exec, s[30:31]
	s_cbranch_vccnz .Lqe_col
	v_mov_b32_e32 v132, 0x3e38aa3b
	v_mov_b32_e32 v133, 0x3e38aa3b
	v_mov_b32_e32 v134, 0x3e38aa3b
	v_mov_b32_e32 v135, 0x3e38aa3b
	v_mov_b32_e32 v136, 0x3e38aa3b
	v_mov_b32_e32 v137, 0x3e38aa3b
	v_mov_b32_e32 v138, 0x3e38aa3b
	v_mov_b32_e32 v139, 0x3e38aa3b
	v_mov_b32_e32 v140, 0x3e38aa3b
	v_mov_b32_e32 v141, 0x3e38aa3b
	v_mov_b32_e32 v142, 0x3e38aa3b
	v_mov_b32_e32 v143, 0x3e38aa3b
	v_mov_b32_e32 v144, 0x3e38aa3b
	v_mov_b32_e32 v145, 0x3e38aa3b
	v_mov_b32_e32 v146, 0x3e38aa3b
	v_mov_b32_e32 v147, 0x3e38aa3b
; __device__ __forceinline__ unsigned cvtpk(float lo, float hi) { f32x2 v = {lo, hi}; bf16x2_t b = __builtin_convertvector(v, bf16x2_t); return __builtin_bit_cast(unsigned, b); }
;     __device__ __forceinline__ void operator()(const f32x4 (&acc)[2][2][4][2], const Unit& u, int wr, int wc, int fr, int fq) const {
;     ...
;                 bf16_t* rowp = base + (size_t)(row0 + ai * HALF + m * 16) * 1024 + colbase;
;                 {   const f32x4 v0 = acc[ai][0][m][0] * mul * g00, v1 = acc[ai][0][m][1] * mul * g01;
;                     u32x4 w; w.x = cvtpk(v0[0], v0[1]); w.y = cvtpk(v0[2], v0[3]); w.z = cvtpk(v1[0], v1[1]); w.w = cvtpk(v1[2], v1[3]);
;                     *(u32x4*)(rowp) = w; }
;                 {   const f32x4 v0 = acc[ai][1][m][0] * mul * g10, v1 = acc[ai][1][m][1] * mul * g11;
;                     u32x4 w; w.x = cvtpk(v0[0], v0[1]); w.y = cvtpk(v0[2], v0[3]); w.z = cvtpk(v1[0], v1[1]); w.w = cvtpk(v1[2], v1[3]);
;                     *(u32x4*)(rowp + 32) = w; }
.Lqe_col:
	v_pk_mul_f32 v[128:129], v[128:129], v[148:149] op_sel_hi:[1,0]
	v_pk_mul_f32 v[130:131], v[130:131], v[148:149] op_sel_hi:[1,0]
	v_pk_mul_f32 v[124:125], v[124:125], v[148:149] op_sel_hi:[1,0]
	v_pk_mul_f32 v[126:127], v[126:127], v[148:149] op_sel_hi:[1,0]
	v_pk_mul_f32 v[120:121], v[120:121], v[148:149] op_sel_hi:[1,0]
	v_pk_mul_f32 v[122:123], v[122:123], v[148:149] op_sel_hi:[1,0]
	v_pk_mul_f32 v[116:117], v[116:117], v[148:149] op_sel_hi:[1,0]
	v_pk_mul_f32 v[118:119], v[118:119], v[148:149] op_sel_hi:[1,0]
	v_pk_mul_f32 v[128:129], v[132:133], v[128:129]
	v_pk_mul_f32 v[130:131], v[134:135], v[130:131]
	v_pk_mul_f32 v[124:125], v[136:137], v[124:125]
	v_pk_mul_f32 v[126:127], v[138:139], v[126:127]
	v_pk_mul_f32 v[120:121], v[140:141], v[120:121]
	v_pk_mul_f32 v[122:123], v[142:143], v[122:123]
	v_pk_mul_f32 v[116:117], v[144:145], v[116:117]
	v_pk_mul_f32 v[118:119], v[146:147], v[118:119]
	v_cvt_pk_bf16_f32 v128, v128, v129
	v_cvt_pk_bf16_f32 v129, v130, v131
	v_cvt_pk_bf16_f32 v130, v124, v125
	v_cvt_pk_bf16_f32 v131, v126, v127
	global_store_dwordx4 v[166:167], v[128:131], off
	v_cvt_pk_bf16_f32 v120, v120, v121
	v_cvt_pk_bf16_f32 v121, v122, v123
	v_cvt_pk_bf16_f32 v122, v116, v117
	v_cvt_pk_bf16_f32 v123, v118, v119
	global_store_dwordx4 v[166:167], v[120:123], off offset:64
	v_pk_mul_f32 v[112:113], v[112:113], v[150:151] op_sel_hi:[1,0]
	v_pk_mul_f32 v[114:115], v[114:115], v[150:151] op_sel_hi:[1,0]
	v_pk_mul_f32 v[108:109], v[108:109], v[150:151] op_sel_hi:[1,0]
	v_pk_mul_f32 v[110:111], v[110:111], v[150:151] op_sel_hi:[1,0]
	v_pk_mul_f32 v[104:105], v[104:105], v[150:151] op_sel_hi:[1,0]
	v_pk_mul_f32 v[106:107], v[106:107], v[150:151] op_sel_hi:[1,0]
	v_pk_mul_f32 v[100:101], v[100:101], v[150:151] op_sel_hi:[1,0]
	v_pk_mul_f32 v[102:103], v[102:103], v[150:151] op_sel_hi:[1,0]
	s_mov_b32 s100, 0x8000
	v_lshl_add_u64 v[192:193], v[166:167], 0, s[100:101]
	v_pk_mul_f32 v[112:113], v[132:133], v[112:113]
	v_pk_mul_f32 v[114:115], v[134:135], v[114:115]
	v_pk_mul_f32 v[108:109], v[136:137], v[108:109]
	v_pk_mul_f32 v[110:111], v[138:139], v[110:111]
	v_pk_mul_f32 v[104:105], v[140:141], v[104:105]
	v_pk_mul_f32 v[106:107], v[142:143], v[106:107]
	v_pk_mul_f32 v[100:101], v[144:145], v[100:101]
	v_pk_mul_f32 v[102:103], v[146:147], v[102:103]
	v_cvt_pk_bf16_f32 v112, v112, v113
	v_cvt_pk_bf16_f32 v113, v114, v115
	v_cvt_pk_bf16_f32 v114, v108, v109
	v_cvt_pk_bf16_f32 v115, v110, v111
	global_store_dwordx4 v[192:193], v[112:115], off
	v_cvt_pk_bf16_f32 v104, v104, v105
	v_cvt_pk_bf16_f32 v105, v106, v107
	v_cvt_pk_bf16_f32 v106, v100, v101
	v_cvt_pk_bf16_f32 v107, v102, v103
	global_store_dwordx4 v[192:193], v[104:107], off offset:64
	v_pk_mul_f32 v[96:97], v[96:97], v[152:153] op_sel_hi:[1,0]
	v_pk_mul_f32 v[98:99], v[98:99], v[152:153] op_sel_hi:[1,0]
	v_pk_mul_f32 v[92:93], v[92:93], v[152:153] op_sel_hi:[1,0]
	v_pk_mul_f32 v[94:95], v[94:95], v[152:153] op_sel_hi:[1,0]
	v_pk_mul_f32 v[88:89], v[88:89], v[152:153] op_sel_hi:[1,0]
	v_pk_mul_f32 v[90:91], v[90:91], v[152:153] op_sel_hi:[1,0]
	v_pk_mul_f32 v[84:85], v[84:85], v[152:153] op_sel_hi:[1,0]
	v_pk_mul_f32 v[86:87], v[86:87], v[152:153] op_sel_hi:[1,0]
	s_mov_b32 s100, 0x10000
	v_lshl_add_u64 v[192:193], v[166:167], 0, s[100:101]
	v_pk_mul_f32 v[96:97], v[132:133], v[96:97]
	v_pk_mul_f32 v[98:99], v[134:135], v[98:99]
	v_pk_mul_f32 v[92:93], v[136:137], v[92:93]
	v_pk_mul_f32 v[94:95], v[138:139], v[94:95]
	v_pk_mul_f32 v[88:89], v[140:141], v[88:89]
	v_pk_mul_f32 v[90:91], v[142:143], v[90:91]
	v_pk_mul_f32 v[84:85], v[144:145], v[84:85]
	v_pk_mul_f32 v[86:87], v[146:147], v[86:87]
	v_cvt_pk_bf16_f32 v96, v96, v97
	v_cvt_pk_bf16_f32 v97, v98, v99
	v_cvt_pk_bf16_f32 v98, v92, v93
	v_cvt_pk_bf16_f32 v99, v94, v95
	global_store_dwordx4 v[192:193], v[96:99], off
	v_cvt_pk_bf16_f32 v88, v88, v89
	v_cvt_pk_bf16_f32 v89, v90, v91
	v_cvt_pk_bf16_f32 v90, v84, v85
	v_cvt_pk_bf16_f32 v91, v86, v87
	global_store_dwordx4 v[192:193], v[88:91], off offset:64
	v_pk_mul_f32 v[80:81], v[80:81], v[154:155] op_sel_hi:[1,0]
	v_pk_mul_f32 v[82:83], v[82:83], v[154:155] op_sel_hi:[1,0]
	v_pk_mul_f32 v[76:77], v[76:77], v[154:155] op_sel_hi:[1,0]
	v_pk_mul_f32 v[78:79], v[78:79], v[154:155] op_sel_hi:[1,0]
	v_pk_mul_f32 v[72:73], v[72:73], v[154:155] op_sel_hi:[1,0]
	v_pk_mul_f32 v[74:75], v[74:75], v[154:155] op_sel_hi:[1,0]
	v_pk_mul_f32 v[68:69], v[68:69], v[154:155] op_sel_hi:[1,0]
	v_pk_mul_f32 v[70:71], v[70:71], v[154:155] op_sel_hi:[1,0]
	s_mov_b32 s100, 0x18000
	v_lshl_add_u64 v[192:193], v[166:167], 0, s[100:101]
	v_pk_mul_f32 v[80:81], v[132:133], v[80:81]
	v_pk_mul_f32 v[82:83], v[134:135], v[82:83]
	v_pk_mul_f32 v[76:77], v[136:137], v[76:77]
	v_pk_mul_f32 v[78:79], v[138:139], v[78:79]
	v_pk_mul_f32 v[72:73], v[140:141], v[72:73]
	v_pk_mul_f32 v[74:75], v[142:143], v[74:75]
	v_pk_mul_f32 v[68:69], v[144:145], v[68:69]
	v_pk_mul_f32 v[70:71], v[146:147], v[70:71]
	v_cvt_pk_bf16_f32 v80, v80, v81
	v_cvt_pk_bf16_f32 v81, v82, v83
	v_cvt_pk_bf16_f32 v82, v76, v77
	v_cvt_pk_bf16_f32 v83, v78, v79
	global_store_dwordx4 v[192:193], v[80:83], off
	v_cvt_pk_bf16_f32 v72, v72, v73
	v_cvt_pk_bf16_f32 v73, v74, v75
	v_cvt_pk_bf16_f32 v74, v68, v69
	v_cvt_pk_bf16_f32 v75, v70, v71
	global_store_dwordx4 v[192:193], v[72:75], off offset:64
	v_pk_mul_f32 v[64:65], v[64:65], v[156:157] op_sel_hi:[1,0]
	v_pk_mul_f32 v[66:67], v[66:67], v[156:157] op_sel_hi:[1,0]
	v_pk_mul_f32 v[60:61], v[60:61], v[156:157] op_sel_hi:[1,0]
	v_pk_mul_f32 v[62:63], v[62:63], v[156:157] op_sel_hi:[1,0]
	v_pk_mul_f32 v[56:57], v[56:57], v[156:157] op_sel_hi:[1,0]
	v_pk_mul_f32 v[58:59], v[58:59], v[156:157] op_sel_hi:[1,0]
; __device__ __forceinline__ unsigned cvtpk(float lo, float hi) { f32x2 v = {lo, hi}; bf16x2_t b = __builtin_convertvector(v, bf16x2_t); return __builtin_bit_cast(unsigned, b); }
;     __device__ __forceinline__ void operator()(const f32x4 (&acc)[2][2][4][2], const Unit& u, int wr, int wc, int fr, int fq) const {
;     ...
;                 bf16_t* rowp = base + (size_t)(row0 + ai * HALF + m * 16) * 1024 + colbase;
;                 {   const f32x4 v0 = acc[ai][0][m][0] * mul * g00, v1 = acc[ai][0][m][1] * mul * g01;
;                     u32x4 w; w.x = cvtpk(v0[0], v0[1]); w.y = cvtpk(v0[2], v0[3]); w.z = cvtpk(v1[0], v1[1]); w.w = cvtpk(v1[2], v1[3]);
;                     *(u32x4*)(rowp) = w; }
;                 {   const f32x4 v0 = acc[ai][1][m][0] * mul * g10, v1 = acc[ai][1][m][1] * mul * g11;
;                     u32x4 w; w.x = cvtpk(v0[0], v0[1]); w.y = cvtpk(v0[2], v0[3]); w.z = cvtpk(v1[0], v1[1]); w.w = cvtpk(v1[2], v1[3]);
;                     *(u32x4*)(rowp + 32) = w; }
	v_pk_mul_f32 v[52:53], v[52:53], v[156:157] op_sel_hi:[1,0]
	v_pk_mul_f32 v[54:55], v[54:55], v[156:157] op_sel_hi:[1,0]
	s_mov_b32 s100, 0x40000
	v_lshl_add_u64 v[192:193], v[166:167], 0, s[100:101]
	v_pk_mul_f32 v[64:65], v[132:133], v[64:65]
	v_pk_mul_f32 v[66:67], v[134:135], v[66:67]
	v_pk_mul_f32 v[60:61], v[136:137], v[60:61]
	v_pk_mul_f32 v[62:63], v[138:139], v[62:63]
	v_pk_mul_f32 v[56:57], v[140:141], v[56:57]
	v_pk_mul_f32 v[58:59], v[142:143], v[58:59]
	v_pk_mul_f32 v[52:53], v[144:145], v[52:53]
	v_pk_mul_f32 v[54:55], v[146:147], v[54:55]
	v_cvt_pk_bf16_f32 v64, v64, v65
	v_cvt_pk_bf16_f32 v65, v66, v67
	v_cvt_pk_bf16_f32 v66, v60, v61
	v_cvt_pk_bf16_f32 v67, v62, v63
	global_store_dwordx4 v[192:193], v[64:67], off
	v_cvt_pk_bf16_f32 v56, v56, v57
	v_cvt_pk_bf16_f32 v57, v58, v59
	v_cvt_pk_bf16_f32 v58, v52, v53
	v_cvt_pk_bf16_f32 v59, v54, v55
	global_store_dwordx4 v[192:193], v[56:59], off offset:64
	v_pk_mul_f32 v[48:49], v[48:49], v[158:159] op_sel_hi:[1,0]
	v_pk_mul_f32 v[50:51], v[50:51], v[158:159] op_sel_hi:[1,0]
	v_pk_mul_f32 v[44:45], v[44:45], v[158:159] op_sel_hi:[1,0]
	v_pk_mul_f32 v[46:47], v[46:47], v[158:159] op_sel_hi:[1,0]
	v_pk_mul_f32 v[40:41], v[40:41], v[158:159] op_sel_hi:[1,0]
	v_pk_mul_f32 v[42:43], v[42:43], v[158:159] op_sel_hi:[1,0]
	v_pk_mul_f32 v[36:37], v[36:37], v[158:159] op_sel_hi:[1,0]
	v_pk_mul_f32 v[38:39], v[38:39], v[158:159] op_sel_hi:[1,0]
	s_mov_b32 s100, 0x48000
	v_lshl_add_u64 v[192:193], v[166:167], 0, s[100:101]
	v_pk_mul_f32 v[48:49], v[132:133], v[48:49]
	v_pk_mul_f32 v[50:51], v[134:135], v[50:51]
	v_pk_mul_f32 v[44:45], v[136:137], v[44:45]
	v_pk_mul_f32 v[46:47], v[138:139], v[46:47]
	v_pk_mul_f32 v[40:41], v[140:141], v[40:41]
	v_pk_mul_f32 v[42:43], v[142:143], v[42:43]
	v_pk_mul_f32 v[36:37], v[144:145], v[36:37]
	v_pk_mul_f32 v[38:39], v[146:147], v[38:39]
	v_cvt_pk_bf16_f32 v48, v48, v49
	v_cvt_pk_bf16_f32 v49, v50, v51
	v_cvt_pk_bf16_f32 v50, v44, v45
	v_cvt_pk_bf16_f32 v51, v46, v47
	global_store_dwordx4 v[192:193], v[48:51], off
	v_cvt_pk_bf16_f32 v40, v40, v41
	v_cvt_pk_bf16_f32 v41, v42, v43
	v_cvt_pk_bf16_f32 v42, v36, v37
	v_cvt_pk_bf16_f32 v43, v38, v39
	global_store_dwordx4 v[192:193], v[40:43], off offset:64
	v_pk_mul_f32 v[32:33], v[32:33], v[160:161] op_sel_hi:[1,0]
	v_pk_mul_f32 v[34:35], v[34:35], v[160:161] op_sel_hi:[1,0]
	v_pk_mul_f32 v[28:29], v[28:29], v[160:161] op_sel_hi:[1,0]
	v_pk_mul_f32 v[30:31], v[30:31], v[160:161] op_sel_hi:[1,0]
	v_pk_mul_f32 v[24:25], v[24:25], v[160:161] op_sel_hi:[1,0]
	v_pk_mul_f32 v[26:27], v[26:27], v[160:161] op_sel_hi:[1,0]
	v_pk_mul_f32 v[20:21], v[20:21], v[160:161] op_sel_hi:[1,0]
	v_pk_mul_f32 v[22:23], v[22:23], v[160:161] op_sel_hi:[1,0]
	s_mov_b32 s100, 0x50000
	v_lshl_add_u64 v[192:193], v[166:167], 0, s[100:101]
	v_pk_mul_f32 v[32:33], v[132:133], v[32:33]
	v_pk_mul_f32 v[34:35], v[134:135], v[34:35]
	v_pk_mul_f32 v[28:29], v[136:137], v[28:29]
	v_pk_mul_f32 v[30:31], v[138:139], v[30:31]
	v_pk_mul_f32 v[24:25], v[140:141], v[24:25]
	v_pk_mul_f32 v[26:27], v[142:143], v[26:27]
	v_pk_mul_f32 v[20:21], v[144:145], v[20:21]
	v_pk_mul_f32 v[22:23], v[146:147], v[22:23]
	v_cvt_pk_bf16_f32 v32, v32, v33
	v_cvt_pk_bf16_f32 v33, v34, v35
	v_cvt_pk_bf16_f32 v34, v28, v29
	v_cvt_pk_bf16_f32 v35, v30, v31
	global_store_dwordx4 v[192:193], v[32:35], off
	v_cvt_pk_bf16_f32 v24, v24, v25
	v_cvt_pk_bf16_f32 v25, v26, v27
	v_cvt_pk_bf16_f32 v26, v20, v21
	v_cvt_pk_bf16_f32 v27, v22, v23
	global_store_dwordx4 v[192:193], v[24:27], off offset:64
	v_pk_mul_f32 v[16:17], v[16:17], v[162:163] op_sel_hi:[1,0]
	v_pk_mul_f32 v[18:19], v[18:19], v[162:163] op_sel_hi:[1,0]
	v_pk_mul_f32 v[12:13], v[12:13], v[162:163] op_sel_hi:[1,0]
	v_pk_mul_f32 v[14:15], v[14:15], v[162:163] op_sel_hi:[1,0]
	v_pk_mul_f32 v[8:9], v[8:9], v[162:163] op_sel_hi:[1,0]
	v_pk_mul_f32 v[10:11], v[10:11], v[162:163] op_sel_hi:[1,0]
	v_pk_mul_f32 v[4:5], v[4:5], v[162:163] op_sel_hi:[1,0]
	v_pk_mul_f32 v[6:7], v[6:7], v[162:163] op_sel_hi:[1,0]
	s_mov_b32 s100, 0x58000
	v_lshl_add_u64 v[192:193], v[166:167], 0, s[100:101]
	v_pk_mul_f32 v[16:17], v[132:133], v[16:17]
	v_pk_mul_f32 v[18:19], v[134:135], v[18:19]
	v_pk_mul_f32 v[12:13], v[136:137], v[12:13]
	v_pk_mul_f32 v[14:15], v[138:139], v[14:15]
	v_pk_mul_f32 v[8:9], v[140:141], v[8:9]
	v_pk_mul_f32 v[10:11], v[142:143], v[10:11]
	v_pk_mul_f32 v[4:5], v[144:145], v[4:5]
	v_pk_mul_f32 v[6:7], v[146:147], v[6:7]
	v_cvt_pk_bf16_f32 v16, v16, v17
	v_cvt_pk_bf16_f32 v17, v18, v19
	v_cvt_pk_bf16_f32 v18, v12, v13
	v_cvt_pk_bf16_f32 v19, v14, v15
	global_store_dwordx4 v[192:193], v[16:19], off
	v_cvt_pk_bf16_f32 v8, v8, v9
	v_cvt_pk_bf16_f32 v9, v10, v11
	v_cvt_pk_bf16_f32 v10, v4, v5
	v_cvt_pk_bf16_f32 v11, v6, v7
	global_store_dwordx4 v[192:193], v[8:11], off offset:64
	s_branch .Lqe_tail
; __device__ __forceinline__ unsigned cvtpk(float lo, float hi) { f32x2 v = {lo, hi}; bf16x2_t b = __builtin_convertvector(v, bf16x2_t); return __builtin_bit_cast(unsigned, b); }
;     __device__ __forceinline__ void operator()(const f32x4 (&acc)[2][2][4][2], const Unit& u, int wr, int wc, int fr, int fq) const {
;     ...
;                 bf16_t* rowp = base + (size_t)(row0 + ai * HALF + m * 16) * 1024 + colbase;
;                 {   const f32x4 v0 = acc[ai][0][m][0] * mul * g00, v1 = acc[ai][0][m][1] * mul * g01;
;                     u32x4 w; w.x = cvtpk(v0[0], v0[1]); w.y = cvtpk(v0[2], v0[3]); w.z = cvtpk(v1[0], v1[1]); w.w = cvtpk(v1[2], v1[3]);
;                     *(u32x4*)(rowp) = w; }
;                 {   const f32x4 v0 = acc[ai][1][m][0] * mul * g10, v1 = acc[ai][1][m][1] * mul * g11;
;                     u32x4 w; w.x = cvtpk(v0[0], v0[1]); w.y = cvtpk(v0[2], v0[3]); w.z = cvtpk(v1[0], v1[1]); w.w = cvtpk(v1[2], v1[3]);
;                     *(u32x4*)(rowp + 32) = w; }
.Lqe_plain:
	v_pk_mul_f32 v[128:129], v[128:129], v[148:149] op_sel_hi:[1,0]
	v_pk_mul_f32 v[130:131], v[130:131], v[148:149] op_sel_hi:[1,0]
	v_pk_mul_f32 v[124:125], v[124:125], v[148:149] op_sel_hi:[1,0]
	v_pk_mul_f32 v[126:127], v[126:127], v[148:149] op_sel_hi:[1,0]
	v_pk_mul_f32 v[120:121], v[120:121], v[148:149] op_sel_hi:[1,0]
	v_pk_mul_f32 v[122:123], v[122:123], v[148:149] op_sel_hi:[1,0]
	v_pk_mul_f32 v[116:117], v[116:117], v[148:149] op_sel_hi:[1,0]
	v_pk_mul_f32 v[118:119], v[118:119], v[148:149] op_sel_hi:[1,0]
	v_cvt_pk_bf16_f32 v128, v128, v129
	v_cvt_pk_bf16_f32 v129, v130, v131
	v_cvt_pk_bf16_f32 v130, v124, v125
	v_cvt_pk_bf16_f32 v131, v126, v127
	global_store_dwordx4 v[166:167], v[128:131], off
	v_cvt_pk_bf16_f32 v120, v120, v121
	v_cvt_pk_bf16_f32 v121, v122, v123
	v_cvt_pk_bf16_f32 v122, v116, v117
	v_cvt_pk_bf16_f32 v123, v118, v119
	global_store_dwordx4 v[166:167], v[120:123], off offset:64
	v_pk_mul_f32 v[112:113], v[112:113], v[150:151] op_sel_hi:[1,0]
	v_pk_mul_f32 v[114:115], v[114:115], v[150:151] op_sel_hi:[1,0]
	v_pk_mul_f32 v[108:109], v[108:109], v[150:151] op_sel_hi:[1,0]
	v_pk_mul_f32 v[110:111], v[110:111], v[150:151] op_sel_hi:[1,0]
	v_pk_mul_f32 v[104:105], v[104:105], v[150:151] op_sel_hi:[1,0]
	v_pk_mul_f32 v[106:107], v[106:107], v[150:151] op_sel_hi:[1,0]
	v_pk_mul_f32 v[100:101], v[100:101], v[150:151] op_sel_hi:[1,0]
	v_pk_mul_f32 v[102:103], v[102:103], v[150:151] op_sel_hi:[1,0]
	s_mov_b32 s100, 0x8000
	v_lshl_add_u64 v[192:193], v[166:167], 0, s[100:101]
	v_cvt_pk_bf16_f32 v112, v112, v113
	v_cvt_pk_bf16_f32 v113, v114, v115
	v_cvt_pk_bf16_f32 v114, v108, v109
	v_cvt_pk_bf16_f32 v115, v110, v111
	global_store_dwordx4 v[192:193], v[112:115], off
	v_cvt_pk_bf16_f32 v104, v104, v105
	v_cvt_pk_bf16_f32 v105, v106, v107
	v_cvt_pk_bf16_f32 v106, v100, v101
	v_cvt_pk_bf16_f32 v107, v102, v103
	global_store_dwordx4 v[192:193], v[104:107], off offset:64
	v_pk_mul_f32 v[96:97], v[96:97], v[152:153] op_sel_hi:[1,0]
	v_pk_mul_f32 v[98:99], v[98:99], v[152:153] op_sel_hi:[1,0]
	v_pk_mul_f32 v[92:93], v[92:93], v[152:153] op_sel_hi:[1,0]
	v_pk_mul_f32 v[94:95], v[94:95], v[152:153] op_sel_hi:[1,0]
	v_pk_mul_f32 v[88:89], v[88:89], v[152:153] op_sel_hi:[1,0]
	v_pk_mul_f32 v[90:91], v[90:91], v[152:153] op_sel_hi:[1,0]
	v_pk_mul_f32 v[84:85], v[84:85], v[152:153] op_sel_hi:[1,0]
	v_pk_mul_f32 v[86:87], v[86:87], v[152:153] op_sel_hi:[1,0]
	s_mov_b32 s100, 0x10000
	v_lshl_add_u64 v[192:193], v[166:167], 0, s[100:101]
	v_cvt_pk_bf16_f32 v96, v96, v97
	v_cvt_pk_bf16_f32 v97, v98, v99
	v_cvt_pk_bf16_f32 v98, v92, v93
	v_cvt_pk_bf16_f32 v99, v94, v95
	global_store_dwordx4 v[192:193], v[96:99], off
	v_cvt_pk_bf16_f32 v88, v88, v89
	v_cvt_pk_bf16_f32 v89, v90, v91
	v_cvt_pk_bf16_f32 v90, v84, v85
	v_cvt_pk_bf16_f32 v91, v86, v87
	global_store_dwordx4 v[192:193], v[88:91], off offset:64
	v_pk_mul_f32 v[80:81], v[80:81], v[154:155] op_sel_hi:[1,0]
	v_pk_mul_f32 v[82:83], v[82:83], v[154:155] op_sel_hi:[1,0]
	v_pk_mul_f32 v[76:77], v[76:77], v[154:155] op_sel_hi:[1,0]
	v_pk_mul_f32 v[78:79], v[78:79], v[154:155] op_sel_hi:[1,0]
	v_pk_mul_f32 v[72:73], v[72:73], v[154:155] op_sel_hi:[1,0]
	v_pk_mul_f32 v[74:75], v[74:75], v[154:155] op_sel_hi:[1,0]
	v_pk_mul_f32 v[68:69], v[68:69], v[154:155] op_sel_hi:[1,0]
	v_pk_mul_f32 v[70:71], v[70:71], v[154:155] op_sel_hi:[1,0]
	s_mov_b32 s100, 0x18000
	v_lshl_add_u64 v[192:193], v[166:167], 0, s[100:101]
	v_cvt_pk_bf16_f32 v80, v80, v81
	v_cvt_pk_bf16_f32 v81, v82, v83
	v_cvt_pk_bf16_f32 v82, v76, v77
	v_cvt_pk_bf16_f32 v83, v78, v79
	global_store_dwordx4 v[192:193], v[80:83], off
	v_cvt_pk_bf16_f32 v72, v72, v73
	v_cvt_pk_bf16_f32 v73, v74, v75
	v_cvt_pk_bf16_f32 v74, v68, v69
	v_cvt_pk_bf16_f32 v75, v70, v71
	global_store_dwordx4 v[192:193], v[72:75], off offset:64
	v_pk_mul_f32 v[64:65], v[64:65], v[156:157] op_sel_hi:[1,0]
; __device__ __forceinline__ unsigned cvtpk(float lo, float hi) { f32x2 v = {lo, hi}; bf16x2_t b = __builtin_convertvector(v, bf16x2_t); return __builtin_bit_cast(unsigned, b); }
; #define PG8_BAR __builtin_amdgcn_s_barrier()
;     __device__ __forceinline__ void operator()(const f32x4 (&acc)[2][2][4][2], const Unit& u, int wr, int wc, int fr, int fq) const {
;     ...
;                 bf16_t* rowp = base + (size_t)(row0 + ai * HALF + m * 16) * 1024 + colbase;
;                 {   const f32x4 v0 = acc[ai][0][m][0] * mul * g00, v1 = acc[ai][0][m][1] * mul * g01;
;                     u32x4 w; w.x = cvtpk(v0[0], v0[1]); w.y = cvtpk(v0[2], v0[3]); w.z = cvtpk(v1[0], v1[1]); w.w = cvtpk(v1[2], v1[3]);
;                     *(u32x4*)(rowp) = w; }
;                 {   const f32x4 v0 = acc[ai][1][m][0] * mul * g10, v1 = acc[ai][1][m][1] * mul * g11;
;                     u32x4 w; w.x = cvtpk(v0[0], v0[1]); w.y = cvtpk(v0[2], v0[3]); w.z = cvtpk(v1[0], v1[1]); w.w = cvtpk(v1[2], v1[3]);
;                     *(u32x4*)(rowp + 32) = w; }
; template <class Epi, class Sched, bool ALIGN_EPI = false, bool SP2 = false>
; __device__ __forceinline__ void gemm_phase(PG8_LAS unsigned char* lds, const Gemm g, const Sched& S, const Epi& E) {
;     ...
;         if constexpr (ALIGN_EPI) { if (wr == 0) PG8_BAR; }
;         if constexpr (!Epi::AFTER_DRAIN) { E(acc, cur, wr, wc, fr, fq); S.done(cur); }
;         if (!has_next) break;
	v_pk_mul_f32 v[66:67], v[66:67], v[156:157] op_sel_hi:[1,0]
	v_pk_mul_f32 v[60:61], v[60:61], v[156:157] op_sel_hi:[1,0]
	v_pk_mul_f32 v[62:63], v[62:63], v[156:157] op_sel_hi:[1,0]
	v_pk_mul_f32 v[56:57], v[56:57], v[156:157] op_sel_hi:[1,0]
	v_pk_mul_f32 v[58:59], v[58:59], v[156:157] op_sel_hi:[1,0]
	v_pk_mul_f32 v[52:53], v[52:53], v[156:157] op_sel_hi:[1,0]
	v_pk_mul_f32 v[54:55], v[54:55], v[156:157] op_sel_hi:[1,0]
	s_mov_b32 s100, 0x40000
	v_lshl_add_u64 v[192:193], v[166:167], 0, s[100:101]
	v_cvt_pk_bf16_f32 v64, v64, v65
	v_cvt_pk_bf16_f32 v65, v66, v67
	v_cvt_pk_bf16_f32 v66, v60, v61
	v_cvt_pk_bf16_f32 v67, v62, v63
	global_store_dwordx4 v[192:193], v[64:67], off
	v_cvt_pk_bf16_f32 v56, v56, v57
	v_cvt_pk_bf16_f32 v57, v58, v59
	v_cvt_pk_bf16_f32 v58, v52, v53
	v_cvt_pk_bf16_f32 v59, v54, v55
	global_store_dwordx4 v[192:193], v[56:59], off offset:64
	v_pk_mul_f32 v[48:49], v[48:49], v[158:159] op_sel_hi:[1,0]
	v_pk_mul_f32 v[50:51], v[50:51], v[158:159] op_sel_hi:[1,0]
	v_pk_mul_f32 v[44:45], v[44:45], v[158:159] op_sel_hi:[1,0]
	v_pk_mul_f32 v[46:47], v[46:47], v[158:159] op_sel_hi:[1,0]
	v_pk_mul_f32 v[40:41], v[40:41], v[158:159] op_sel_hi:[1,0]
	v_pk_mul_f32 v[42:43], v[42:43], v[158:159] op_sel_hi:[1,0]
	v_pk_mul_f32 v[36:37], v[36:37], v[158:159] op_sel_hi:[1,0]
	v_pk_mul_f32 v[38:39], v[38:39], v[158:159] op_sel_hi:[1,0]
	s_mov_b32 s100, 0x48000
	v_lshl_add_u64 v[192:193], v[166:167], 0, s[100:101]
	v_cvt_pk_bf16_f32 v48, v48, v49
	v_cvt_pk_bf16_f32 v49, v50, v51
	v_cvt_pk_bf16_f32 v50, v44, v45
	v_cvt_pk_bf16_f32 v51, v46, v47
	global_store_dwordx4 v[192:193], v[48:51], off
	v_cvt_pk_bf16_f32 v40, v40, v41
	v_cvt_pk_bf16_f32 v41, v42, v43
	v_cvt_pk_bf16_f32 v42, v36, v37
	v_cvt_pk_bf16_f32 v43, v38, v39
	global_store_dwordx4 v[192:193], v[40:43], off offset:64
	v_pk_mul_f32 v[32:33], v[32:33], v[160:161] op_sel_hi:[1,0]
	v_pk_mul_f32 v[34:35], v[34:35], v[160:161] op_sel_hi:[1,0]
	v_pk_mul_f32 v[28:29], v[28:29], v[160:161] op_sel_hi:[1,0]
	v_pk_mul_f32 v[30:31], v[30:31], v[160:161] op_sel_hi:[1,0]
	v_pk_mul_f32 v[24:25], v[24:25], v[160:161] op_sel_hi:[1,0]
	v_pk_mul_f32 v[26:27], v[26:27], v[160:161] op_sel_hi:[1,0]
	v_pk_mul_f32 v[20:21], v[20:21], v[160:161] op_sel_hi:[1,0]
	v_pk_mul_f32 v[22:23], v[22:23], v[160:161] op_sel_hi:[1,0]
	s_mov_b32 s100, 0x50000
	v_lshl_add_u64 v[192:193], v[166:167], 0, s[100:101]
	v_cvt_pk_bf16_f32 v32, v32, v33
	v_cvt_pk_bf16_f32 v33, v34, v35
	v_cvt_pk_bf16_f32 v34, v28, v29
	v_cvt_pk_bf16_f32 v35, v30, v31
	global_store_dwordx4 v[192:193], v[32:35], off
	v_cvt_pk_bf16_f32 v24, v24, v25
	v_cvt_pk_bf16_f32 v25, v26, v27
	v_cvt_pk_bf16_f32 v26, v20, v21
	v_cvt_pk_bf16_f32 v27, v22, v23
	global_store_dwordx4 v[192:193], v[24:27], off offset:64
	v_pk_mul_f32 v[16:17], v[16:17], v[162:163] op_sel_hi:[1,0]
	v_pk_mul_f32 v[18:19], v[18:19], v[162:163] op_sel_hi:[1,0]
	v_pk_mul_f32 v[12:13], v[12:13], v[162:163] op_sel_hi:[1,0]
	v_pk_mul_f32 v[14:15], v[14:15], v[162:163] op_sel_hi:[1,0]
	v_pk_mul_f32 v[8:9], v[8:9], v[162:163] op_sel_hi:[1,0]
	v_pk_mul_f32 v[10:11], v[10:11], v[162:163] op_sel_hi:[1,0]
	v_pk_mul_f32 v[4:5], v[4:5], v[162:163] op_sel_hi:[1,0]
	v_pk_mul_f32 v[6:7], v[6:7], v[162:163] op_sel_hi:[1,0]
	s_mov_b32 s100, 0x58000
	v_lshl_add_u64 v[192:193], v[166:167], 0, s[100:101]
	v_cvt_pk_bf16_f32 v16, v16, v17
	v_cvt_pk_bf16_f32 v17, v18, v19
	v_cvt_pk_bf16_f32 v18, v12, v13
	v_cvt_pk_bf16_f32 v19, v14, v15
	global_store_dwordx4 v[192:193], v[16:19], off
	v_cvt_pk_bf16_f32 v8, v8, v9
	v_cvt_pk_bf16_f32 v9, v10, v11
	v_cvt_pk_bf16_f32 v10, v4, v5
	v_cvt_pk_bf16_f32 v11, v6, v7
	global_store_dwordx4 v[192:193], v[8:11], off offset:64
.Lqe_tail:
	s_andn2_b64 vcc, exec, s[4:5]
	s_mov_b64 s[4:5], -1
	s_cbranch_vccnz .LBB0_96
	s_andn2_b64 vcc, exec, s[12:13]
	s_cbranch_vccnz .LBB0_95
	s_barrier
	s_branch .LBB0_95
